# attention: s_setprio 1/0 around the QK and PV MFMA chains (wave priority ping-pong) on top of v_n9
# speedup vs baseline: 1.0121x; 1.0046x over previous
; __device__ __forceinline__ int crow(int r, int hi) { return (r & 3) + 8 * (r >> 2) + 4 * hi; }
; __device__ __forceinline__ void sb_half(f32x16& pz, float& run, bool need_mask, int kb, int t, int hi) {
;     ...
;   for (int r = 0; r < 16; ++r) {
;     const float e = __builtin_amdgcn_exp2f(fminf(pz[r] * C2, 60.f));
;     l[r] = __builtin_amdgcn_rcpf(1.f + e);
;     pz[r] = e;
;   }
;   if (need_mask) {
; #pragma unroll
;     for (int r = 0; r < 16; ++r) { if (kb + crow(r, hi) >= t) { l[r] = 1.f; pz[r] = 0.f; } }
;   }
; __device__ __forceinline__ void attn_phase(const Params& p, char* smem, int bid, int nblk) {
;     ...
;         if (k0 + 32 <= tmax) {
;           f32x16 pz;
; #pragma unroll
;           for (int r = 0; r < 16; ++r) pz[r] = 0.f;
; #pragma unroll
;           for (int d0 = 0; d0 < 8; ++d0) {
;             const bf16x8 kf = *(const bf16x8*)(K_lds + KSWZ(32 + r32, (d0 * 16 + hi * 8) * 2));
;             pz = __builtin_amdgcn_mfma_f32_32x32x16_bf16(kf, qr[d0], pz, 0, 0, 0);
;           }
;           sb_half(pz, run, k0 + 63 >= tmin, k0 + 32, t, hi);
.LBB0_1790:
	s_sub_i32 s0, s55, 63
	s_lshl_b32 s56, s53, 15
	v_cmp_le_i32_e32 vcc, s0, v173
	s_and_saveexec_b64 s[44:45], vcc
	s_cbranch_execz .LBB0_1802
	s_sub_i32 s0, s55, 31
	v_add_u32_e32 v64, s56, v194
	v_cmp_le_i32_e32 vcc, s0, v173
	v_add_u32_e32 v186, v64, v205
	v_add_u32_e32 v185, v64, v206
	v_add_u32_e32 v184, v64, v207
	v_add_u32_e32 v183, v64, v208
	v_add_u32_e32 v182, v64, v209
	v_add_u32_e32 v181, v64, v210
	v_add_u32_e32 v180, v64, v211
	v_add_u32_e32 v175, v64, v212
	s_and_saveexec_b64 s[48:49], vcc
	s_cbranch_execz .Lattn_zero
	ds_read_b128 v[64:67], v186 offset:8192
	ds_read_b128 v[144:147], v185 offset:8192
	v_cmp_ge_i32_e32 vcc, s55, v230
	s_waitcnt lgkmcnt(1)
	s_setprio 1
	v_mfma_f32_32x32x16_bf16 v[64:79], v[64:67], v[80:83], 0
	s_waitcnt lgkmcnt(0)
	v_mfma_f32_32x32x16_bf16 v[64:79], v[144:147], v[84:87], v[64:79]
	ds_read_b128 v[144:147], v184 offset:8192
	ds_read_b128 v[148:151], v183 offset:8192
	s_waitcnt lgkmcnt(1)
	v_mfma_f32_32x32x16_bf16 v[64:79], v[144:147], v[88:91], v[64:79]
	s_waitcnt lgkmcnt(0)
	v_mfma_f32_32x32x16_bf16 v[64:79], v[148:151], v[92:95], v[64:79]
	ds_read_b128 v[144:147], v182 offset:8192
	ds_read_b128 v[148:151], v181 offset:8192
	s_waitcnt lgkmcnt(1)
	v_mfma_f32_32x32x16_bf16 v[64:79], v[144:147], v[96:99], v[64:79]
	s_waitcnt lgkmcnt(0)
	v_mfma_f32_32x32x16_bf16 v[64:79], v[148:151], v[100:103], v[64:79]
	ds_read_b128 v[144:147], v180 offset:8192
	ds_read_b128 v[148:151], v175 offset:8192
	s_waitcnt lgkmcnt(1)
	v_mfma_f32_32x32x16_bf16 v[64:79], v[144:147], v[104:107], v[64:79]
	s_waitcnt lgkmcnt(0)
	v_mfma_f32_32x32x16_bf16 v[64:79], v[148:151], v[108:111], v[64:79]
	s_setprio 0
	s_nop 11
	v_mul_f32_e32 v64, 0x3e0293ee, v64
	v_mul_f32_e32 v67, 0x3e0293ee, v67
	v_mul_f32_e32 v68, 0x3e0293ee, v68
	v_mul_f32_e32 v71, 0x3e0293ee, v71
	v_min_f32_e32 v64, 0x42700000, v64
	v_min_f32_e32 v67, 0x42700000, v67
	v_min_f32_e32 v68, 0x42700000, v68
	v_min_f32_e32 v144, 0x42700000, v71
	v_exp_f32_e32 v71, v64
	v_exp_f32_e32 v187, v67
	v_exp_f32_e32 v234, v68
	v_mul_f32_e32 v66, 0x3e0293ee, v66
	v_mul_f32_e32 v72, 0x3e0293ee, v72
	v_mul_f32_e32 v74, 0x3e0293ee, v74
	v_mul_f32_e32 v75, 0x3e0293ee, v75
	v_mul_f32_e32 v76, 0x3e0293ee, v76
	v_min_f32_e32 v66, 0x42700000, v66
	v_min_f32_e32 v72, 0x42700000, v72
	v_mul_f32_e32 v70, 0x3e0293ee, v70
	v_mul_f32_e32 v73, 0x3e0293ee, v73
	v_mul_f32_e32 v77, 0x3e0293ee, v77
	v_min_f32_e32 v74, 0x42700000, v74
	v_min_f32_e32 v75, 0x42700000, v75
	v_min_f32_e32 v76, 0x42700000, v76
	v_exp_f32_e32 v178, v66
	v_exp_f32_e32 v235, v72
	v_add_f32_e32 v66, 1.0, v71
	v_add_f32_e32 v72, 1.0, v187
	v_mul_f32_e32 v65, 0x3e0293ee, v65
	v_min_f32_e32 v70, 0x42700000, v70
	v_min_f32_e32 v145, 0x42700000, v73
	v_min_f32_e32 v77, 0x42700000, v77
	v_exp_f32_e32 v231, v144
	v_exp_f32_e32 v64, v74
	v_exp_f32_e32 v232, v75
	v_exp_f32_e32 v237, v76
	v_add_f32_e32 v75, 1.0, v234
	v_rcp_f32_e32 v74, v66
	v_rcp_f32_e32 v66, v72
	v_mul_f32_e32 v72, 0x3e0293ee, v78
	v_mul_f32_e32 v69, 0x3e0293ee, v69
	v_min_f32_e32 v65, 0x42700000, v65
	v_exp_f32_e32 v70, v70
	v_exp_f32_e32 v67, v145
	v_exp_f32_e32 v236, v77
	v_rcp_f32_e32 v77, v75
	v_min_f32_e32 v72, 0x42700000, v72
	v_mul_f32_e32 v75, 0x3e0293ee, v79
	v_min_f32_e32 v69, 0x42700000, v69
	v_exp_f32_e32 v65, v65
	v_exp_f32_e32 v72, v72
	v_min_f32_e32 v75, 0x42700000, v75
	v_exp_f32_e32 v73, v69
	v_add_f32_e32 v69, 1.0, v178
	v_exp_f32_e32 v78, v75
	v_add_f32_e32 v147, 1.0, v231
	v_rcp_f32_e32 v144, v69
	v_add_f32_e32 v69, 1.0, v237
	v_add_f32_e32 v146, 1.0, v70
	v_add_f32_e32 v148, 1.0, v235
	v_add_f32_e32 v149, 1.0, v67
	v_rcp_f32_e32 v233, v147
	v_rcp_f32_e32 v147, v69
	v_add_f32_e32 v69, 1.0, v236
	v_add_f32_e32 v68, 1.0, v65
	v_add_f32_e32 v151, 1.0, v232
	v_rcp_f32_e32 v238, v146
	v_rcp_f32_e32 v146, v148
	v_rcp_f32_e32 v148, v149
	v_rcp_f32_e32 v149, v69
	v_add_f32_e32 v69, 1.0, v72
	v_add_f32_e32 v145, 1.0, v73
	v_add_f32_e32 v150, 1.0, v64
	v_rcp_f32_e32 v76, v68
	v_rcp_f32_e32 v68, v151
	v_rcp_f32_e32 v151, v69
	v_add_f32_e32 v69, 1.0, v78
	v_rcp_f32_e32 v145, v145
	v_rcp_f32_e32 v150, v150
	v_rcp_f32_e32 v69, v69
	s_and_saveexec_b64 s[50:51], vcc
	s_cbranch_execz .LBB0_1796
; __device__ __forceinline__ int crow(int r, int hi) { return (r & 3) + 8 * (r >> 2) + 4 * hi; }
; __device__ __forceinline__ void sb_half(f32x16& pz, float& run, bool need_mask, int kb, int t, int hi) {
;     ...
;   if (need_mask) {
; #pragma unroll
;     for (int r = 0; r < 16; ++r) { if (kb + crow(r, hi) >= t) { l[r] = 1.f; pz[r] = 0.f; } }
;   }
	v_add_u32_e32 v75, s55, v195
	v_subrev_u32_e32 v79, 31, v75
	v_cmp_lt_i32_e32 vcc, v79, v174
	v_subrev_u32_e32 v79, 30, v75
	v_cmp_lt_i32_e64 s[0:1], v79, v174
	v_subrev_u32_e32 v79, 29, v75
	v_cmp_lt_i32_e64 s[6:7], v79, v174
	v_subrev_u32_e32 v79, 28, v75
	v_cmp_lt_i32_e64 s[8:9], v79, v174
	v_subrev_u32_e32 v79, 23, v75
	v_cmp_lt_i32_e64 s[10:11], v79, v174
	v_subrev_u32_e32 v79, 22, v75
	v_cmp_lt_i32_e64 s[12:13], v79, v174
	v_subrev_u32_e32 v79, 21, v75
	v_cmp_lt_i32_e64 s[14:15], v79, v174
	v_subrev_u32_e32 v79, 20, v75
	v_cmp_lt_i32_e64 s[16:17], v79, v174
	v_add_u32_e32 v79, -15, v75
	v_cmp_lt_i32_e64 s[18:19], v79, v174
	v_add_u32_e32 v79, -14, v75
	v_cmp_lt_i32_e64 s[20:21], v79, v174
	v_add_u32_e32 v79, -13, v75
	v_cmp_lt_i32_e64 s[22:23], v79, v174
	v_add_u32_e32 v79, -12, v75
	v_cmp_lt_i32_e64 s[24:25], v79, v174
	v_add_u32_e32 v79, -7, v75
	v_cmp_lt_i32_e64 s[26:27], v79, v174
	v_add_u32_e32 v79, -6, v75
	v_cmp_lt_i32_e64 s[28:29], v79, v174
	v_add_u32_e32 v79, -5, v75
	v_cmp_lt_i32_e64 s[30:31], v79, v174
	s_or_b64 s[28:29], s[30:31], s[28:29]
	s_or_b64 s[26:27], s[28:29], s[26:27]
	s_or_b64 s[24:25], s[26:27], s[24:25]
	s_or_b64 s[22:23], s[24:25], s[22:23]
	s_or_b64 s[20:21], s[22:23], s[20:21]
	s_or_b64 s[18:19], s[20:21], s[18:19]
	s_or_b64 s[16:17], s[18:19], s[16:17]
	s_or_b64 s[14:15], s[16:17], s[14:15]
	s_or_b64 s[12:13], s[14:15], s[12:13]
	s_or_b64 s[10:11], s[12:13], s[10:11]
	s_or_b64 s[8:9], s[10:11], s[8:9]
	s_or_b64 s[6:7], s[8:9], s[6:7]
	s_or_b64 s[0:1], s[6:7], s[0:1]
	s_or_b64 vcc, s[0:1], vcc
	v_add_u32_e32 v75, -4, v75
	v_cndmask_b32_e64 v72, 0, v72, s[30:31]
	v_cndmask_b32_e64 v236, 0, v236, s[28:29]
	v_cndmask_b32_e64 v237, 0, v237, s[26:27]
	v_cndmask_b32_e64 v232, 0, v232, s[24:25]
	v_cndmask_b32_e64 v64, 0, v64, s[22:23]
	v_cndmask_b32_e64 v67, 0, v67, s[20:21]
	v_cndmask_b32_e64 v235, 0, v235, s[18:19]
	v_cndmask_b32_e64 v231, 0, v231, s[16:17]
	v_cndmask_b32_e64 v70, 0, v70, s[14:15]
	v_cndmask_b32_e64 v73, 0, v73, s[12:13]
	v_cndmask_b32_e64 v234, 0, v234, s[10:11]
	v_cndmask_b32_e64 v187, 0, v187, s[8:9]
	v_cndmask_b32_e64 v178, 0, v178, s[6:7]
	v_cndmask_b32_e64 v65, 0, v65, s[0:1]
	v_cndmask_b32_e32 v71, 0, v71, vcc
	v_cndmask_b32_e64 v149, 1.0, v149, s[28:29]
	v_cndmask_b32_e64 v147, 1.0, v147, s[26:27]
	v_cndmask_b32_e64 v68, 1.0, v68, s[24:25]
	v_cndmask_b32_e64 v150, 1.0, v150, s[22:23]
	v_cndmask_b32_e64 v148, 1.0, v148, s[20:21]
	v_cndmask_b32_e64 v146, 1.0, v146, s[18:19]
	v_cndmask_b32_e64 v233, 1.0, v233, s[16:17]
	v_cndmask_b32_e64 v238, 1.0, v238, s[14:15]
	v_cndmask_b32_e64 v145, 1.0, v145, s[12:13]
	v_cndmask_b32_e64 v77, 1.0, v77, s[10:11]
	v_cndmask_b32_e64 v66, 1.0, v66, s[8:9]
	v_cndmask_b32_e64 v144, 1.0, v144, s[6:7]
	v_cndmask_b32_e64 v76, 1.0, v76, s[0:1]
	v_cndmask_b32_e32 v74, 1.0, v74, vcc
	v_cndmask_b32_e64 v151, 1.0, v151, s[30:31]
	v_cmp_ge_i32_e32 vcc, v75, v174
	s_and_saveexec_b64 s[0:1], vcc
	v_mov_b32_e32 v78, 0
	v_mov_b32_e32 v69, 1.0
	s_or_b64 exec, exec, s[0:1]

; __device__ __forceinline__ int crow(int r, int hi) { return (r & 3) + 8 * (r >> 2) + 4 * hi; }
; __device__ __forceinline__ void sb_half(f32x16& pz, float& run, bool need_mask, int kb, int t, int hi) {
;     ...
;   for (int r = 0; r < 16; ++r) {
;     const float e = __builtin_amdgcn_exp2f(fminf(pz[r] * C2, 60.f));
;     l[r] = __builtin_amdgcn_rcpf(1.f + e);
;     pz[r] = e;
;   }
;   if (need_mask) {
; #pragma unroll
;     for (int r = 0; r < 16; ++r) { if (kb + crow(r, hi) >= t) { l[r] = 1.f; pz[r] = 0.f; } }
;   }
; __device__ __forceinline__ void attn_phase(const Params& p, char* smem, int bid, int nblk) {
;     ...
;         {
;           f32x16 pz;
; #pragma unroll
;           for (int r = 0; r < 16; ++r) pz[r] = 0.f;
; #pragma unroll
;           for (int d0 = 0; d0 < 8; ++d0) {
;             const bf16x8 kf = *(const bf16x8*)(K_lds + KSWZ(r32, (d0 * 16 + hi * 8) * 2));
;             pz = __builtin_amdgcn_mfma_f32_32x32x16_bf16(kf, qr[d0], pz, 0, 0, 0);
;           }
;           sb_half(pz, run, k0 + 31 >= tmin, k0, t, hi);
.LBB0_1797:
	s_or_b64 exec, exec, s[48:49]
	ds_read_b128 v[64:67], v186
	ds_read_b128 v[232:235], v185
	s_sub_i32 s0, s55, 32
	v_cmp_ge_i32_e32 vcc, s0, v230
	s_waitcnt lgkmcnt(1)
	s_setprio 1
	v_mfma_f32_32x32x16_bf16 v[64:79], v[64:67], v[80:83], 0
	s_waitcnt lgkmcnt(0)
	v_mfma_f32_32x32x16_bf16 v[64:79], v[232:235], v[84:87], v[64:79]
	ds_read_b128 v[184:187], v184
	ds_read_b128 v[232:235], v183
	s_waitcnt lgkmcnt(1)
	v_mfma_f32_32x32x16_bf16 v[64:79], v[184:187], v[88:91], v[64:79]
	s_waitcnt lgkmcnt(0)
	v_mfma_f32_32x32x16_bf16 v[64:79], v[232:235], v[92:95], v[64:79]
	ds_read_b128 v[182:185], v182
	ds_read_b128 v[232:235], v181
	s_waitcnt lgkmcnt(1)
	v_mfma_f32_32x32x16_bf16 v[64:79], v[182:185], v[96:99], v[64:79]
	ds_read_b128 v[180:183], v180
	ds_read_b128 v[184:187], v175
	s_waitcnt lgkmcnt(2)
	v_mfma_f32_32x32x16_bf16 v[64:79], v[232:235], v[100:103], v[64:79]
	s_waitcnt lgkmcnt(1)
	v_mfma_f32_32x32x16_bf16 v[64:79], v[180:183], v[104:107], v[64:79]
	s_waitcnt lgkmcnt(0)
	v_mfma_f32_32x32x16_bf16 v[64:79], v[184:187], v[108:111], v[64:79]
	s_setprio 0
	s_nop 11
	v_mul_f32_e32 v64, 0x3e0293ee, v64
	v_mul_f32_e32 v67, 0x3e0293ee, v67
	v_mul_f32_e32 v68, 0x3e0293ee, v68
	v_mul_f32_e32 v71, 0x3e0293ee, v71
	v_min_f32_e32 v64, 0x42700000, v64
	v_min_f32_e32 v67, 0x42700000, v67
	v_min_f32_e32 v68, 0x42700000, v68
	v_min_f32_e32 v180, 0x42700000, v71
	v_exp_f32_e32 v71, v64
	v_exp_f32_e32 v175, v67
	v_exp_f32_e32 v234, v68
	v_mul_f32_e32 v66, 0x3e0293ee, v66
	v_mul_f32_e32 v72, 0x3e0293ee, v72
	v_mul_f32_e32 v74, 0x3e0293ee, v74
	v_mul_f32_e32 v75, 0x3e0293ee, v75
	v_mul_f32_e32 v76, 0x3e0293ee, v76
	v_min_f32_e32 v66, 0x42700000, v66
	v_min_f32_e32 v72, 0x42700000, v72
	v_mul_f32_e32 v70, 0x3e0293ee, v70
	v_mul_f32_e32 v73, 0x3e0293ee, v73
	v_mul_f32_e32 v77, 0x3e0293ee, v77
	v_min_f32_e32 v74, 0x42700000, v74
	v_min_f32_e32 v75, 0x42700000, v75
	v_min_f32_e32 v76, 0x42700000, v76
	v_exp_f32_e32 v178, v66
	v_exp_f32_e32 v235, v72
	v_add_f32_e32 v66, 1.0, v71
	v_add_f32_e32 v72, 1.0, v175
	v_mul_f32_e32 v65, 0x3e0293ee, v65
	v_min_f32_e32 v70, 0x42700000, v70
	v_min_f32_e32 v181, 0x42700000, v73
	v_min_f32_e32 v77, 0x42700000, v77
	v_exp_f32_e32 v231, v180
	v_exp_f32_e32 v64, v74
	v_exp_f32_e32 v232, v75
	v_exp_f32_e32 v237, v76
	v_add_f32_e32 v75, 1.0, v234
	v_rcp_f32_e32 v74, v66
	v_rcp_f32_e32 v66, v72
	v_mul_f32_e32 v72, 0x3e0293ee, v78
	v_mul_f32_e32 v69, 0x3e0293ee, v69
	v_min_f32_e32 v65, 0x42700000, v65
	v_exp_f32_e32 v70, v70
	v_exp_f32_e32 v67, v181
	v_exp_f32_e32 v236, v77
	v_rcp_f32_e32 v77, v75
	v_min_f32_e32 v72, 0x42700000, v72
	v_mul_f32_e32 v75, 0x3e0293ee, v79
	v_min_f32_e32 v69, 0x42700000, v69
	v_exp_f32_e32 v65, v65
	v_exp_f32_e32 v72, v72
	v_min_f32_e32 v75, 0x42700000, v75
	v_exp_f32_e32 v73, v69
	v_add_f32_e32 v69, 1.0, v178
	v_exp_f32_e32 v78, v75
	v_add_f32_e32 v183, 1.0, v231
	v_rcp_f32_e32 v180, v69
	v_add_f32_e32 v69, 1.0, v237
	v_add_f32_e32 v182, 1.0, v70
	v_add_f32_e32 v184, 1.0, v235
	v_add_f32_e32 v185, 1.0, v67
	v_rcp_f32_e32 v233, v183
	v_rcp_f32_e32 v183, v69
	v_add_f32_e32 v69, 1.0, v236
	v_add_f32_e32 v68, 1.0, v65
	v_add_f32_e32 v187, 1.0, v232
	v_rcp_f32_e32 v238, v182
	v_rcp_f32_e32 v182, v184
	v_rcp_f32_e32 v184, v185
	v_rcp_f32_e32 v185, v69
	v_add_f32_e32 v69, 1.0, v72
	v_add_f32_e32 v181, 1.0, v73
	v_add_f32_e32 v186, 1.0, v64
	v_rcp_f32_e32 v76, v68
	v_rcp_f32_e32 v68, v187
	v_rcp_f32_e32 v187, v69
	v_add_f32_e32 v69, 1.0, v78
	v_rcp_f32_e32 v181, v181
	v_rcp_f32_e32 v186, v186
	v_rcp_f32_e32 v69, v69
	s_and_saveexec_b64 s[48:49], vcc
	s_cbranch_execz .LBB0_1801
	v_add_u32_e32 v75, s55, v195
	v_subrev_u32_e32 v79, 63, v75
	v_cmp_lt_i32_e32 vcc, v79, v174
	v_subrev_u32_e32 v79, 62, v75
	v_cmp_lt_i32_e64 s[0:1], v79, v174
	v_subrev_u32_e32 v79, 61, v75
	v_cmp_lt_i32_e64 s[6:7], v79, v174
	v_subrev_u32_e32 v79, 60, v75
	v_cmp_lt_i32_e64 s[8:9], v79, v174
	v_subrev_u32_e32 v79, 55, v75
	v_cmp_lt_i32_e64 s[10:11], v79, v174
	v_subrev_u32_e32 v79, 54, v75
	v_cmp_lt_i32_e64 s[12:13], v79, v174
	v_subrev_u32_e32 v79, 53, v75
	v_cmp_lt_i32_e64 s[14:15], v79, v174
	v_subrev_u32_e32 v79, 52, v75
	v_cmp_lt_i32_e64 s[16:17], v79, v174
	v_subrev_u32_e32 v79, 47, v75
	v_cmp_lt_i32_e64 s[18:19], v79, v174
	v_subrev_u32_e32 v79, 46, v75
	v_cmp_lt_i32_e64 s[20:21], v79, v174
	v_subrev_u32_e32 v79, 45, v75
	v_cmp_lt_i32_e64 s[22:23], v79, v174
	v_subrev_u32_e32 v79, 44, v75
	v_cmp_lt_i32_e64 s[24:25], v79, v174
	v_subrev_u32_e32 v79, 39, v75
	v_cmp_lt_i32_e64 s[26:27], v79, v174
	v_subrev_u32_e32 v79, 38, v75
	v_cmp_lt_i32_e64 s[28:29], v79, v174
	v_subrev_u32_e32 v79, 37, v75
	v_cmp_lt_i32_e64 s[30:31], v79, v174
	s_or_b64 s[28:29], s[30:31], s[28:29]
	s_or_b64 s[26:27], s[28:29], s[26:27]
	s_or_b64 s[24:25], s[26:27], s[24:25]
	s_or_b64 s[22:23], s[24:25], s[22:23]
	s_or_b64 s[20:21], s[22:23], s[20:21]
	s_or_b64 s[18:19], s[20:21], s[18:19]
	s_or_b64 s[16:17], s[18:19], s[16:17]
	s_or_b64 s[14:15], s[16:17], s[14:15]
	s_or_b64 s[12:13], s[14:15], s[12:13]
	s_or_b64 s[10:11], s[12:13], s[10:11]
	s_or_b64 s[8:9], s[10:11], s[8:9]
	s_or_b64 s[6:7], s[8:9], s[6:7]
	s_or_b64 s[0:1], s[6:7], s[0:1]
	s_or_b64 vcc, s[0:1], vcc
	v_subrev_u32_e32 v75, 36, v75
	v_cndmask_b32_e64 v72, 0, v72, s[30:31]
	v_cndmask_b32_e64 v236, 0, v236, s[28:29]
	v_cndmask_b32_e64 v237, 0, v237, s[26:27]
	v_cndmask_b32_e64 v232, 0, v232, s[24:25]
	v_cndmask_b32_e64 v64, 0, v64, s[22:23]
	v_cndmask_b32_e64 v67, 0, v67, s[20:21]
	v_cndmask_b32_e64 v235, 0, v235, s[18:19]
	v_cndmask_b32_e64 v231, 0, v231, s[16:17]
	v_cndmask_b32_e64 v70, 0, v70, s[14:15]
	v_cndmask_b32_e64 v73, 0, v73, s[12:13]
	v_cndmask_b32_e64 v234, 0, v234, s[10:11]
	v_cndmask_b32_e64 v175, 0, v175, s[8:9]
	v_cndmask_b32_e64 v178, 0, v178, s[6:7]
	v_cndmask_b32_e64 v65, 0, v65, s[0:1]
	v_cndmask_b32_e32 v71, 0, v71, vcc
	v_cndmask_b32_e64 v185, 1.0, v185, s[28:29]
	v_cndmask_b32_e64 v183, 1.0, v183, s[26:27]
	v_cndmask_b32_e64 v68, 1.0, v68, s[24:25]
	v_cndmask_b32_e64 v186, 1.0, v186, s[22:23]
	v_cndmask_b32_e64 v184, 1.0, v184, s[20:21]
	v_cndmask_b32_e64 v182, 1.0, v182, s[18:19]
	v_cndmask_b32_e64 v233, 1.0, v233, s[16:17]
	v_cndmask_b32_e64 v238, 1.0, v238, s[14:15]
	v_cndmask_b32_e64 v181, 1.0, v181, s[12:13]
	v_cndmask_b32_e64 v77, 1.0, v77, s[10:11]
	v_cndmask_b32_e64 v66, 1.0, v66, s[8:9]
	v_cndmask_b32_e64 v180, 1.0, v180, s[6:7]
	v_cndmask_b32_e64 v76, 1.0, v76, s[0:1]
	v_cndmask_b32_e32 v74, 1.0, v74, vcc
	v_cndmask_b32_e64 v187, 1.0, v187, s[30:31]
	v_cmp_ge_i32_e32 vcc, v75, v174
	s_and_saveexec_b64 s[0:1], vcc
	v_mov_b32_e32 v78, 0
	v_mov_b32_e32 v69, 1.0
	s_or_b64 exec, exec, s[0:1]
; #define SBAR() __builtin_amdgcn_sched_barrier(0)
; template <int D0> __device__ __forceinline__ void pv_one(f32x16& od, int vb, bf16x8 pa0, bf16x8 pa1, bf16x8 pa2, bf16x8 pa3) {
;   const s16x4 l0 = tr_read<v_rd_off(D0, 0, 0)>(vb), h0 = tr_read<v_rd_off(D0, 0, 1)>(vb), l1 = tr_read<v_rd_off(D0, 1, 0)>(vb), h1 = tr_read<v_rd_off(D0, 1, 1)>(vb);
;   const s16x4 l2 = tr_read<v_rd_off(D0, 2, 0)>(vb), h2 = tr_read<v_rd_off(D0, 2, 1)>(vb), l3 = tr_read<v_rd_off(D0, 3, 0)>(vb), h3 = tr_read<v_rd_off(D0, 3, 1)>(vb);
;   asm volatile("s_waitcnt lgkmcnt(0)" ::: "memory"); SBAR();
;     ...
;   od = __builtin_amdgcn_mfma_f32_32x32x16_bf16(pa0, PK(l0, h0), od, 0, 0, 0);
;   od = __builtin_amdgcn_mfma_f32_32x32x16_bf16(pa1, PK(l1, h1), od, 0, 0, 0);
;   od = __builtin_amdgcn_mfma_f32_32x32x16_bf16(pa2, PK(l2, h2), od, 0, 0, 0);
;   od = __builtin_amdgcn_mfma_f32_32x32x16_bf16(pa3, PK(l3, h3), od, 0, 0, 0);
; __device__ __forceinline__ void sb_half(f32x16& pz, float& run, bool need_mask, int kb, int t, int hi) {
;     ...
; #pragma unroll
;   for (int g = 0; g < 4; ++g) { l[4 * g + 2] *= l[4 * g + 3]; l[4 * g + 1] *= l[4 * g + 2]; l[4 * g] *= l[4 * g + 1]; }
;   const float cs3 = l[12], cs2 = l[8] * cs3, cs1 = l[4] * cs2, cs0 = l[0] * cs1;
;   const float off0 = cs1 * pl32_other(cs0, cs1, hi) * run;
;   const float off1 = cs2 * pl32_other(cs1, cs2, hi) * run;
;   const float off2 = cs3 * pl32_other(cs2, cs3, hi) * run;
;   const float off3 = pl32_other(cs3, 1.f, hi) * run;
;   float tot;
;   { auto rr = __builtin_amdgcn_permlane32_swap(__float_as_uint(cs0), __float_as_uint(cs0), false, false); tot = __uint_as_float(rr[0]) * __uint_as_float(rr[1]); }
; #pragma unroll
;   for (int r = 0; r < 4; ++r) {
;     pz[r] = pz[r] * l[r] * off0; pz[4 + r] = pz[4 + r] * l[4 + r] * off1;
;     pz[8 + r] = pz[8 + r] * l[8 + r] * off2; pz[12 + r] = pz[12 + r] * l[12 + r] * off3;
;   }
;   run *= tot;
; }
.LBB0_1801:
	s_or_b64 exec, exec, s[48:49]
	v_pk_mul_f32 v[186:187], v[186:187], v[68:69]
	v_add_u32_e32 v242, s56, v221
	v_pk_mul_f32 v[184:185], v[184:185], v[186:187]
	s_nop 0
	v_pk_mul_f32 v[182:183], v[182:183], v[184:185]
	v_mul_f32_e32 v184, v67, v184
	v_pk_mul_f32 v[240:241], v[182:183], v[182:183] op_sel:[0,1] op_sel_hi:[1,0]
	v_mov_b32_e32 v239, v183
	v_mov_b32_e32 v79, v240
	s_nop 1
	v_permlane32_swap_b32_e32 v79, v239
	v_mul_f32_e32 v67, v238, v233
	v_cndmask_b32_e64 v79, v79, v239, s[4:5]
	v_pk_mul_f32 v[180:181], v[180:181], v[66:67]
	v_mov_b32_e32 v75, v240
	v_mul_f32_e32 v239, v183, v79
	v_mov_b32_e32 v79, 1.0
	v_mov_b32_e32 v241, v183
	v_pk_mul_f32 v[76:77], v[76:77], v[180:181]
	s_nop 0
	v_permlane32_swap_b32_e32 v241, v79
	v_pk_mul_f32 v[74:75], v[74:75], v[76:77]
	v_cndmask_b32_e64 v241, v241, v79, s[4:5]
	v_mul_f32_e32 v79, v235, v182
	v_mul_f32_e32 v235, v237, v183
	v_pk_mul_f32 v[182:183], v[74:75], v[74:75] op_sel:[0,1] op_sel_hi:[1,0]
	v_mul_f32_e32 v185, v236, v185
	v_mov_b32_e32 v183, v182
	v_mov_b32_e32 v236, v75
	s_nop 1
	v_permlane32_swap_b32_e32 v183, v236
	v_cndmask_b32_e64 v183, v183, v236, s[4:5]
	v_mov_b32_e32 v236, v240
	v_mul_f32_e32 v183, v75, v183
	s_nop 0
	v_permlane32_swap_b32_e32 v75, v236
	v_cndmask_b32_e64 v75, v75, v236, s[4:5]
	v_mul_f32_e32 v75, v240, v75
	v_mul_f32_e32 v236, v71, v74
	v_mov_b32_e32 v71, v179
	v_mov_b32_e32 v74, v67
	v_mul_f32_e32 v73, v73, v181
	v_mov_b32_e32 v181, v183
	v_pk_mul_f32 v[70:71], v[70:71], v[74:75]
	v_mul_f32_e32 v65, v65, v76
	v_pk_mul_f32 v[74:75], v[178:179], v[180:181]
	v_mov_b32_e32 v238, v186
	v_mul_f32_e32 v178, v65, v75
	v_mov_b32_e32 v65, v179
	v_pk_mul_f32 v[64:65], v[64:65], v[238:239]
	v_mul_f32_e32 v77, v234, v77
	v_mul_f32_e32 v181, v64, v65
	v_mul_f32_e32 v64, v175, v66
	v_mul_f32_e32 v66, v64, v75
	v_mul_f32_e32 v64, v231, v233
	v_mul_f32_e32 v67, v77, v71
	v_mul_f32_e32 v76, v73, v71
	v_mul_f32_e32 v70, v70, v71
	v_mov_b32_e32 v73, v179
	v_mov_b32_e32 v240, v187
	v_mul_f32_e32 v71, v64, v71
	v_mul_f32_e32 v64, v232, v68
	v_mul_f32_e32 v77, v236, v75
	v_mul_f32_e32 v74, v74, v75
	v_pk_mul_f32 v[72:73], v[72:73], v[240:241]
	v_mul_f32_e32 v75, v64, v65
	v_mul_f32_e32 v64, v78, v69
	v_mul_f32_e32 v180, v184, v65
	v_mul_f32_e32 v183, v235, v73
	v_mul_f32_e32 v184, v185, v73
	v_mul_f32_e32 v72, v72, v73
	v_mul_f32_e32 v73, v64, v73
	v_mov_b32_e32 v64, v182
	s_nop 1
	v_permlane32_swap_b32_e32 v182, v64
	v_mul_f32_e32 v64, v182, v64
	v_mul_f32_e32 v79, v79, v65
	v_mul_f32_e32 v179, v179, v64
	v_cvt_pk_bf16_f32 v64, v77, v178
	v_cvt_pk_bf16_f32 v65, v74, v66
	v_cvt_pk_bf16_f32 v66, v67, v76
	v_cvt_pk_bf16_f32 v67, v70, v71
	v_cvt_pk_bf16_f32 v68, v79, v180
	v_cvt_pk_bf16_f32 v69, v181, v75
	v_cvt_pk_bf16_f32 v70, v183, v184
	v_cvt_pk_bf16_f32 v71, v72, v73
	ds_read_b64_tr_b16 v[72:73], v242 offset:0
	ds_read_b64_tr_b16 v[74:75], v242 offset:0x800
	ds_read_b64_tr_b16 v[76:77], v242 offset:0x1000
	ds_read_b64_tr_b16 v[78:79], v242 offset:0x1800
	ds_read_b64_tr_b16 v[180:181], v242 offset:0x2000
	ds_read_b64_tr_b16 v[182:183], v242 offset:0x2800
	ds_read_b64_tr_b16 v[184:185], v242 offset:0x3000
	ds_read_b64_tr_b16 v[186:187], v242 offset:0x3800
	s_waitcnt lgkmcnt(0)
	s_nop 0
	v_permlane32_swap_b32_e32 v64, v66
	v_permlane32_swap_b32_e32 v65, v67
	v_permlane32_swap_b32_e32 v68, v70
	v_permlane32_swap_b32_e32 v69, v71
	s_setprio 1
	v_mfma_f32_32x32x16_bf16 v[48:63], v[64:67], v[72:75], v[48:63]
	ds_read_b64_tr_b16 v[72:73], v242 offset:0x200
	ds_read_b64_tr_b16 v[74:75], v242 offset:0xa00
	s_nop 0
	v_mfma_f32_32x32x16_bf16 v[48:63], v[68:71], v[76:79], v[48:63]
	ds_read_b64_tr_b16 v[76:77], v242 offset:0x1200
	ds_read_b64_tr_b16 v[78:79], v242 offset:0x1a00
	v_mfma_f32_32x32x16_bf16 v[48:63], v[144:147], v[180:183], v[48:63]
	ds_read_b64_tr_b16 v[180:181], v242 offset:0x2200
	ds_read_b64_tr_b16 v[182:183], v242 offset:0x2a00
	ds_read_b64_tr_b16 v[232:233], v242 offset:0x3200
	ds_read_b64_tr_b16 v[234:235], v242 offset:0x3a00
	s_waitcnt lgkmcnt(0)
	v_mfma_f32_32x32x16_bf16 v[48:63], v[148:151], v[184:187], v[48:63]
	v_mfma_f32_32x32x16_bf16 v[32:47], v[64:67], v[72:75], v[32:47]
	ds_read_b64_tr_b16 v[72:73], v242 offset:0x400
	ds_read_b64_tr_b16 v[74:75], v242 offset:0xc00
	v_mfma_f32_32x32x16_bf16 v[32:47], v[68:71], v[76:79], v[32:47]
	ds_read_b64_tr_b16 v[76:77], v242 offset:0x1400
	ds_read_b64_tr_b16 v[78:79], v242 offset:0x1c00
	v_mfma_f32_32x32x16_bf16 v[32:47], v[144:147], v[180:183], v[32:47]
	ds_read_b64_tr_b16 v[180:181], v242 offset:0x2400
	ds_read_b64_tr_b16 v[182:183], v242 offset:0x2c00
	ds_read_b64_tr_b16 v[184:185], v242 offset:0x3400
	ds_read_b64_tr_b16 v[186:187], v242 offset:0x3c00
	s_waitcnt lgkmcnt(0)
	v_mfma_f32_32x32x16_bf16 v[32:47], v[148:151], v[232:235], v[32:47]
	v_mfma_f32_32x32x16_bf16 v[16:31], v[64:67], v[72:75], v[16:31]
	ds_read_b64_tr_b16 v[72:73], v242 offset:0x600
	ds_read_b64_tr_b16 v[74:75], v242 offset:0xe00
	v_mfma_f32_32x32x16_bf16 v[16:31], v[68:71], v[76:79], v[16:31]
	ds_read_b64_tr_b16 v[76:77], v242 offset:0x1600
	ds_read_b64_tr_b16 v[78:79], v242 offset:0x1e00
	v_mfma_f32_32x32x16_bf16 v[16:31], v[144:147], v[180:183], v[16:31]
	ds_read_b64_tr_b16 v[180:181], v242 offset:0x2600
	ds_read_b64_tr_b16 v[182:183], v242 offset:0x2e00
	ds_read_b64_tr_b16 v[232:233], v242 offset:0x3600
	ds_read_b64_tr_b16 v[234:235], v242 offset:0x3e00
	s_waitcnt lgkmcnt(0)
	v_mfma_f32_32x32x16_bf16 v[16:31], v[148:151], v[184:187], v[16:31]
	v_mfma_f32_32x32x16_bf16 v[0:15], v[64:67], v[72:75], v[0:15]
	v_mfma_f32_32x32x16_bf16 v[0:15], v[68:71], v[76:79], v[0:15]
	v_mfma_f32_32x32x16_bf16 v[0:15], v[144:147], v[180:183], v[0:15]
	v_mfma_f32_32x32x16_bf16 v[0:15], v[148:151], v[232:235], v[0:15]
	s_setprio 0
